# on top of v135: DA loop K/V tile loads use an SGPR base + 32-bit lane offset (no 64-bit VALU address adds in the loop)
# speedup vs baseline: 1.0095x; 1.0095x over previous
; __device__ void da_unit(char* lds, const Params& p, int layer, int unit) {
;     ...
;     const bf16_t* Kg = p.z + ZS_KD + ((size_t)bh * 2048) * 128 + tid * 8;
;     const bf16_t* Vg = p.vT + VS_VD + ((size_t)bh * 32) * 8192 + tid * 8;
;     ...
;     for (int it = 1; it < NT - qb; ++it) {
;         const int kt = tile_of(it);
;         const char* cK = lds + (it & 1) * DA_STAGE;
;         const char* cV = cK + DA_KBYTES;
;         char* nK = lds + ((it + 1) & 1) * DA_STAGE;
;         const int tn = tile_of(it + 1 < NT ? it + 1 : it);
;         if (it + 1 < NT) {
; #pragma unroll
;             for (int j = 0; j < 4; ++j) rk[j] = *(const u32x4*)(Kg + (size_t)tn * 16384 + j * 4096);
;         }
.Lda_p_noflip:
	v_readfirstlane_b32 s28, v148
	v_readfirstlane_b32 s29, v149
	v_readfirstlane_b32 s30, v150
	v_readfirstlane_b32 s31, v151
	v_and_b32_e32 v251, 63, v187
	v_lshlrev_b32_e32 v251, 4, v251
	s_add_i32 s1, s8, 0x11800
	v_add3_u32 v234, s1, v186, v152
	s_mov_b32 s2, 0x8800
	v_add3_u32 v178, s2, v152, v154
	ds_read_b128 v[210:213], v234 offset:0
	ds_read_b128 v[214:217], v234 offset:32
	ds_read_b128 v[218:221], v234 offset:64
	ds_read_b128 v[222:225], v234 offset:96
	ds_read_b128 v[226:229], v178 offset:18496
	ds_read_b128 v[230:233], v178 offset:23104
	ds_read_b128 v[174:177], v178 offset:27712
	ds_read_b128 v[246:249], v178 offset:32320
	s_add_i32 s0, s14, 2
	s_cmp_lt_u32 2, s9
	s_cselect_b32 s0, s0, 13
	s_lshl_b32 s18, s0, 15
	s_add_u32 s18, s18, s28
	s_addc_u32 s19, s29, 0
	global_load_dwordx4 v[130:133], v251, s[18:19]
	s_add_u32 s18, s18, 0x2000
	s_addc_u32 s19, s19, 0
	global_load_dwordx4 v[134:137], v251, s[18:19]
	s_add_u32 s18, s18, 0x2000
	s_addc_u32 s19, s19, 0
	global_load_dwordx4 v[138:141], v251, s[18:19]
	s_add_u32 s18, s18, 0x2000
	s_addc_u32 s19, s19, 0
	global_load_dwordx4 v[142:145], v251, s[18:19]
	s_waitcnt lgkmcnt(7)
	v_mfma_f32_32x32x16_bf16 v[82:97], v[210:213], v[114:117], v[66:81]
	ds_read_b128 v[210:213], v234 offset:8704
	s_waitcnt lgkmcnt(7)
	v_mfma_f32_32x32x16_bf16 v[82:97], v[214:217], v[118:121], v[82:97]
	ds_read_b128 v[214:217], v234 offset:8736
	s_waitcnt lgkmcnt(7)
	v_mfma_f32_32x32x16_bf16 v[82:97], v[218:221], v[122:125], v[82:97]
	ds_read_b128 v[218:221], v234 offset:8768
	s_waitcnt lgkmcnt(7)
	v_mfma_f32_32x32x16_bf16 v[82:97], v[222:225], v[126:129], v[82:97]
	ds_read_b128 v[222:225], v234 offset:8800
	s_mov_b32 s4, 1
	s_waitcnt lgkmcnt(0)

; __device__ void da_unit(char* lds, const Params& p, int layer, int unit) {
;     ...
;     for (int it = 1; it < NT - qb; ++it) {
;         const int kt = tile_of(it);
;         const char* cK = lds + (it & 1) * DA_STAGE;
;         const char* cV = cK + DA_KBYTES;
;         char* nK = lds + ((it + 1) & 1) * DA_STAGE;
;         const int tn = tile_of(it + 1 < NT ? it + 1 : it);
;         if (it + 1 < NT) {
; #pragma unroll
;             for (int j = 0; j < 4; ++j) rk[j] = *(const u32x4*)(Kg + (size_t)tn * 16384 + j * 4096);
;         }
;     ...
;         DA_FAST_HALF(Bs, -slope2, 0)
;         if (it + 1 < NT) {
; #pragma unroll
;             for (int j = 0; j < 4; ++j) *(u32x4*)(nK + (kr_ + 32 * j) * DA_KP + kc_ * 16) = rk[j];
; #pragma unroll
;             for (int j = 0; j < 4; ++j) rk[j] = *(const u32x4*)(Vg + (size_t)tn * 16384 + j * 4096);
;         }
.Lda_noflip:
	s_add_i32 s0, s14, s4
	s_sub_i32 s1, 15, s4
	s_cmp_lt_u32 s4, s9
	s_cselect_b32 s10, s0, s1
	s_lshl_b32 s11, s10, 7
	s_add_i32 s16, s4, 1
	s_add_i32 s0, s14, s16
	s_sub_i32 s1, 15, s16
	s_cmp_lt_u32 s16, s9
	s_cselect_b32 s0, s0, s1
	s_max_i32 s0, s0, 0
	s_add_i32 s16, s4, 2
	s_add_i32 s3, s14, s16
	s_sub_i32 s1, 15, s16
	s_cmp_lt_u32 s16, s9
	s_cselect_b32 s3, s3, s1
	s_bitcmp1_b32 s4, 0
	s_cselect_b32 s17, 0x11800, 0
	s_sub_i32 s5, 0x11800, s17
	s_add_i32 s1, s17, s8
	s_add_i32 s2, s17, 0x8800
	v_add3_u32 v234, s1, v186, v152
	v_add3_u32 v235, s2, v152, v154
	s_add_i32 s1, s5, s8
	s_add_i32 s2, s5, 0x8800
	v_add3_u32 v236, s1, v186, v152
	v_add3_u32 v178, s2, v152, v154
	v_cvt_f32_u32_e32 v242, s11
	v_add_f32_e32 v242, v185, v242
	v_fma_f32 v239, v242, v250, v169
	v_fma_f32 v253, v242, -v250, v64
	v_sub_f32_e32 v241, v169, v253
	v_mfma_f32_32x32x16_bf16 v[98:113], v[210:213], v[114:117], v[66:81]
	ds_read_b128 v[210:213], v234 offset:17408
	v_sub_f32_e32 v82, v82, v239
	v_sub_f32_e32 v83, v83, v239
	v_sub_f32_e32 v84, v84, v239
	v_sub_f32_e32 v85, v85, v239
	v_exp_f32_e32 v82, v82
	v_mfma_f32_32x32x16_bf16 v[48:63], v[226:229], v[202:205], v[48:63]
	ds_read_b128 v[226:229], v178 offset:18528
	v_exp_f32_e32 v83, v83
	v_exp_f32_e32 v84, v84
	v_exp_f32_e32 v85, v85
	v_mfma_f32_32x32x16_bf16 v[32:47], v[230:233], v[202:205], v[32:47]
	ds_read_b128 v[230:233], v178 offset:23136
	v_add_f32_e32 v191, v191, v82
	v_add_f32_e32 v192, v192, v83
	v_cvt_pk_bf16_f32 v194, v82, v83
	v_add_f32_e32 v191, v191, v84
	v_add_f32_e32 v192, v192, v85
	v_cvt_pk_bf16_f32 v195, v84, v85
	v_mfma_f32_32x32x16_bf16 v[98:113], v[214:217], v[118:121], v[98:113]
	ds_read_b128 v[214:217], v234 offset:17440
	v_sub_f32_e32 v86, v86, v239
	v_sub_f32_e32 v87, v87, v239
	v_sub_f32_e32 v88, v88, v239
	v_sub_f32_e32 v89, v89, v239
	v_exp_f32_e32 v86, v86
	v_mfma_f32_32x32x16_bf16 v[16:31], v[174:177], v[202:205], v[16:31]
	ds_read_b128 v[174:177], v178 offset:27744
	v_exp_f32_e32 v87, v87
	v_exp_f32_e32 v88, v88
	v_exp_f32_e32 v89, v89
	v_mfma_f32_32x32x16_bf16 v[0:15], v[246:249], v[202:205], v[0:15]
	ds_read_b128 v[246:249], v178 offset:32352
	v_add_f32_e32 v191, v191, v86
	v_add_f32_e32 v192, v192, v87
	v_cvt_pk_bf16_f32 v196, v86, v87
	v_add_f32_e32 v191, v191, v88
	v_add_f32_e32 v192, v192, v89
	v_cvt_pk_bf16_f32 v197, v88, v89
	v_mfma_f32_32x32x16_bf16 v[98:113], v[218:221], v[122:125], v[98:113]
	ds_read_b128 v[218:221], v234 offset:17472
	v_sub_f32_e32 v90, v90, v239
	v_sub_f32_e32 v91, v91, v239
	v_sub_f32_e32 v92, v92, v239
	v_sub_f32_e32 v93, v93, v239
	v_exp_f32_e32 v90, v90
	s_waitcnt lgkmcnt(5)
	v_mfma_f32_32x32x16_bf16 v[48:63], v[226:229], v[206:209], v[48:63]
	ds_read_b128 v[226:229], v235 offset:0
	v_exp_f32_e32 v91, v91
	v_exp_f32_e32 v92, v92
	v_exp_f32_e32 v93, v93
	s_waitcnt lgkmcnt(5)
	v_mfma_f32_32x32x16_bf16 v[32:47], v[230:233], v[206:209], v[32:47]
	ds_read_b128 v[230:233], v235 offset:4608
	v_add_f32_e32 v191, v191, v90
	v_add_f32_e32 v192, v192, v91
	v_cvt_pk_bf16_f32 v198, v90, v91
	v_add_f32_e32 v191, v191, v92
	v_add_f32_e32 v192, v192, v93
	v_cvt_pk_bf16_f32 v199, v92, v93
	v_mfma_f32_32x32x16_bf16 v[98:113], v[222:225], v[126:129], v[98:113]
	ds_read_b128 v[222:225], v234 offset:17504
	v_sub_f32_e32 v94, v94, v239
	v_sub_f32_e32 v95, v95, v239
	v_sub_f32_e32 v96, v96, v239
	v_sub_f32_e32 v97, v97, v239
	v_exp_f32_e32 v94, v94
	s_waitcnt lgkmcnt(5)
	v_mfma_f32_32x32x16_bf16 v[16:31], v[174:177], v[206:209], v[16:31]
	ds_read_b128 v[174:177], v235 offset:9216
	v_exp_f32_e32 v95, v95
	v_exp_f32_e32 v96, v96
	v_exp_f32_e32 v97, v97
	s_waitcnt lgkmcnt(5)
	v_mfma_f32_32x32x16_bf16 v[0:15], v[246:249], v[206:209], v[0:15]
	ds_read_b128 v[246:249], v235 offset:13824
	v_add_f32_e32 v191, v191, v94
	v_add_f32_e32 v192, v192, v95
	v_cvt_pk_bf16_f32 v200, v94, v95
	v_add_f32_e32 v191, v191, v96
	v_add_f32_e32 v192, v192, v97
	v_cvt_pk_bf16_f32 v201, v96, v97
	s_waitcnt lgkmcnt(0)
	s_barrier
	v_mfma_f32_32x32x16_bf16 v[82:97], v[210:213], v[114:117], v[66:81]
	ds_read_b128 v[210:213], v234 offset:26112
	v_add3_u32 v158, s5, v180, v182
	v_sub_f32_e32 v98, v98, v241
	v_sub_f32_e32 v99, v99, v241
	v_sub_f32_e32 v100, v100, v241
	v_sub_f32_e32 v101, v101, v241
	v_exp_f32_e32 v98, v98
	v_mfma_f32_32x32x16_bf16 v[48:63], v[226:229], v[194:197], v[48:63]
	ds_read_b128 v[226:229], v235 offset:32
	s_waitcnt vmcnt(3)
	ds_write_b128 v158, v[130:133] offset:0
	s_lshl_b32 s18, s0, 15
	s_add_u32 s18, s18, s30
	s_addc_u32 s19, s31, 0
	global_load_dwordx4 v[130:133], v251, s[18:19]
	v_exp_f32_e32 v99, v99
	v_exp_f32_e32 v100, v100
	v_exp_f32_e32 v101, v101
	v_mfma_f32_32x32x16_bf16 v[32:47], v[230:233], v[194:197], v[32:47]
	ds_read_b128 v[230:233], v235 offset:4640
	v_add_f32_e32 v191, v191, v98
	v_add_f32_e32 v192, v192, v99
	v_cvt_pk_bf16_f32 v202, v98, v99
	v_add_f32_e32 v191, v191, v100
	v_add_f32_e32 v192, v192, v101
	v_cvt_pk_bf16_f32 v203, v100, v101
	v_mfma_f32_32x32x16_bf16 v[82:97], v[214:217], v[118:121], v[82:97]
	ds_read_b128 v[214:217], v234 offset:26144
	s_waitcnt vmcnt(3)
	ds_write_b128 v158, v[134:137] offset:8704
	s_add_u32 s18, s18, 0x2000
	s_addc_u32 s19, s19, 0
	global_load_dwordx4 v[134:137], v251, s[18:19]
	v_sub_f32_e32 v102, v102, v241
	v_sub_f32_e32 v103, v103, v241
	v_sub_f32_e32 v104, v104, v241
	v_sub_f32_e32 v105, v105, v241
	v_exp_f32_e32 v102, v102
	v_mfma_f32_32x32x16_bf16 v[16:31], v[174:177], v[194:197], v[16:31]
	ds_read_b128 v[174:177], v235 offset:9248
	v_exp_f32_e32 v103, v103
	v_exp_f32_e32 v104, v104
	v_exp_f32_e32 v105, v105
	v_mfma_f32_32x32x16_bf16 v[0:15], v[246:249], v[194:197], v[0:15]
	ds_read_b128 v[246:249], v235 offset:13856
	s_waitcnt vmcnt(3)
; __device__ void da_unit(char* lds, const Params& p, int layer, int unit) {
;     ...
;         DA_FAST_HALF(Bs, -slope2, 0)
;         if (it + 1 < NT) {
; #pragma unroll
;             for (int j = 0; j < 4; ++j) *(u32x4*)(nK + (kr_ + 32 * j) * DA_KP + kc_ * 16) = rk[j];
; #pragma unroll
;             for (int j = 0; j < 4; ++j) rk[j] = *(const u32x4*)(Vg + (size_t)tn * 16384 + j * 4096);
;         }
;         DA_FAST_HALF(Bs, -slope2, 1)
;     ...
;         if (it + 1 < NT) {
; #pragma unroll
;             for (int j = 0; j < 4; ++j) *(u32x4*)(nK + DA_KBYTES + (j >> 1) * DA_VSUB + (vr_ + 64 * (j & 1)) * DA_VP + vc_ * 16) = rk[j];
;         }
	ds_write_b128 v158, v[138:141] offset:17408
	s_add_u32 s18, s18, 0x2000
	s_addc_u32 s19, s19, 0
	global_load_dwordx4 v[138:141], v251, s[18:19]
	v_add_f32_e32 v191, v191, v102
	v_add_f32_e32 v192, v192, v103
	v_cvt_pk_bf16_f32 v204, v102, v103
	v_add_f32_e32 v191, v191, v104
	v_add_f32_e32 v192, v192, v105
	v_cvt_pk_bf16_f32 v205, v104, v105
	v_mfma_f32_32x32x16_bf16 v[82:97], v[218:221], v[122:125], v[82:97]
	ds_read_b128 v[218:221], v234 offset:26176
	v_sub_f32_e32 v106, v106, v241
	v_sub_f32_e32 v107, v107, v241
	v_sub_f32_e32 v108, v108, v241
	v_sub_f32_e32 v109, v109, v241
	v_exp_f32_e32 v106, v106
	s_waitcnt lgkmcnt(8)
	v_mfma_f32_32x32x16_bf16 v[48:63], v[226:229], v[198:201], v[48:63]
	ds_read_b128 v[226:229], v235 offset:64
	s_waitcnt vmcnt(3)
	ds_write_b128 v158, v[142:145] offset:26112
	s_add_u32 s18, s18, 0x2000
	s_addc_u32 s19, s19, 0
	global_load_dwordx4 v[142:145], v251, s[18:19]
	v_exp_f32_e32 v107, v107
	v_exp_f32_e32 v108, v108
	v_exp_f32_e32 v109, v109
	s_waitcnt lgkmcnt(8)
	v_mfma_f32_32x32x16_bf16 v[32:47], v[230:233], v[198:201], v[32:47]
	ds_read_b128 v[230:233], v235 offset:4672
	v_add_f32_e32 v191, v191, v106
	v_add_f32_e32 v192, v192, v107
	v_cvt_pk_bf16_f32 v206, v106, v107
	v_add_f32_e32 v191, v191, v108
	v_add_f32_e32 v192, v192, v109
	v_cvt_pk_bf16_f32 v207, v108, v109
	v_mfma_f32_32x32x16_bf16 v[82:97], v[222:225], v[126:129], v[82:97]
	ds_read_b128 v[222:225], v234 offset:26208
	v_sub_f32_e32 v110, v110, v241
	v_sub_f32_e32 v111, v111, v241
	v_sub_f32_e32 v112, v112, v241
	v_sub_f32_e32 v113, v113, v241
	v_exp_f32_e32 v110, v110
	s_waitcnt lgkmcnt(7)
	v_mfma_f32_32x32x16_bf16 v[16:31], v[174:177], v[198:201], v[16:31]
	ds_read_b128 v[174:177], v235 offset:9280
	v_exp_f32_e32 v111, v111
	v_exp_f32_e32 v112, v112
	v_exp_f32_e32 v113, v113
	s_waitcnt lgkmcnt(7)
	v_mfma_f32_32x32x16_bf16 v[0:15], v[246:249], v[198:201], v[0:15]
	ds_read_b128 v[246:249], v235 offset:13888
	v_add_f32_e32 v191, v191, v110
	v_add_f32_e32 v192, v192, v111
	v_cvt_pk_bf16_f32 v208, v110, v111
	v_add_f32_e32 v191, v191, v112
	v_add_f32_e32 v192, v192, v113
	v_cvt_pk_bf16_f32 v209, v112, v113
	s_or_b32 s2, s11, 64
	v_cvt_f32_u32_e32 v242, s2
	v_add_f32_e32 v242, v185, v242
	v_fma_f32 v239, v242, v250, v169
	v_fma_f32 v253, v242, -v250, v64
	v_sub_f32_e32 v241, v169, v253
	v_mfma_f32_32x32x16_bf16 v[98:113], v[210:213], v[114:117], v[66:81]
	v_sub_f32_e32 v82, v82, v239
	v_sub_f32_e32 v83, v83, v239
	v_sub_f32_e32 v84, v84, v239
	v_sub_f32_e32 v85, v85, v239
	v_exp_f32_e32 v82, v82
	s_waitcnt lgkmcnt(5)
	v_mfma_f32_32x32x16_bf16 v[48:63], v[226:229], v[202:205], v[48:63]
	ds_read_b128 v[226:229], v235 offset:96
	v_exp_f32_e32 v83, v83
	v_exp_f32_e32 v84, v84
	v_exp_f32_e32 v85, v85
	s_waitcnt lgkmcnt(4)
	v_mfma_f32_32x32x16_bf16 v[32:47], v[230:233], v[202:205], v[32:47]
	ds_read_b128 v[230:233], v235 offset:4704
	v_add_f32_e32 v191, v191, v82
	v_add_f32_e32 v192, v192, v83
	v_cvt_pk_bf16_f32 v194, v82, v83
	v_add_f32_e32 v191, v191, v84
	v_add_f32_e32 v192, v192, v85
	v_cvt_pk_bf16_f32 v195, v84, v85
	v_mfma_f32_32x32x16_bf16 v[98:113], v[214:217], v[118:121], v[98:113]
	v_sub_f32_e32 v86, v86, v239
	v_sub_f32_e32 v87, v87, v239
	v_sub_f32_e32 v88, v88, v239
	v_sub_f32_e32 v89, v89, v239
	v_exp_f32_e32 v86, v86
	s_waitcnt lgkmcnt(3)
	v_mfma_f32_32x32x16_bf16 v[16:31], v[174:177], v[202:205], v[16:31]
	ds_read_b128 v[174:177], v235 offset:9312
	v_exp_f32_e32 v87, v87
	v_exp_f32_e32 v88, v88
	v_exp_f32_e32 v89, v89
	s_waitcnt lgkmcnt(3)
	v_mfma_f32_32x32x16_bf16 v[0:15], v[246:249], v[202:205], v[0:15]
	ds_read_b128 v[246:249], v235 offset:13920
	v_add3_u32 v158, s5, v183, v181
	v_add_f32_e32 v191, v191, v86
	v_add_f32_e32 v192, v192, v87
	v_cvt_pk_bf16_f32 v196, v86, v87
	v_add_f32_e32 v191, v191, v88
	v_add_f32_e32 v192, v192, v89
	v_cvt_pk_bf16_f32 v197, v88, v89
	v_mfma_f32_32x32x16_bf16 v[98:113], v[218:221], v[122:125], v[98:113]
	s_waitcnt vmcnt(3)
	ds_write_b128 v158, v[130:133] offset:34816
	v_sub_f32_e32 v90, v90, v239
	v_sub_f32_e32 v91, v91, v239
	v_sub_f32_e32 v92, v92, v239
	v_sub_f32_e32 v93, v93, v239
	v_exp_f32_e32 v90, v90
	s_waitcnt lgkmcnt(4)
	v_mfma_f32_32x32x16_bf16 v[48:63], v[226:229], v[206:209], v[48:63]
	ds_read_b128 v[226:229], v235 offset:18432
	s_waitcnt vmcnt(2)
	ds_write_b128 v158, v[134:137] offset:44032
	v_exp_f32_e32 v91, v91
	v_exp_f32_e32 v92, v92
	v_exp_f32_e32 v93, v93
	s_waitcnt lgkmcnt(5)
	v_mfma_f32_32x32x16_bf16 v[32:47], v[230:233], v[206:209], v[32:47]
	ds_read_b128 v[230:233], v235 offset:23040
	s_waitcnt vmcnt(1)
	ds_write_b128 v158, v[138:141] offset:53248
	v_add_f32_e32 v191, v191, v90
	v_add_f32_e32 v192, v192, v91
	v_cvt_pk_bf16_f32 v198, v90, v91
	v_add_f32_e32 v191, v191, v92
	v_add_f32_e32 v192, v192, v93
	v_cvt_pk_bf16_f32 v199, v92, v93
	v_mfma_f32_32x32x16_bf16 v[98:113], v[222:225], v[126:129], v[98:113]
	s_waitcnt vmcnt(0)
	ds_write_b128 v158, v[142:145] offset:62464
	v_sub_f32_e32 v94, v94, v239
	v_sub_f32_e32 v95, v95, v239
	v_sub_f32_e32 v96, v96, v239
	v_sub_f32_e32 v97, v97, v239
	v_exp_f32_e32 v94, v94
	s_waitcnt lgkmcnt(7)
	v_mfma_f32_32x32x16_bf16 v[16:31], v[174:177], v[206:209], v[16:31]
	ds_read_b128 v[174:177], v235 offset:27648
	v_exp_f32_e32 v95, v95
	v_exp_f32_e32 v96, v96
	v_exp_f32_e32 v97, v97
	s_waitcnt lgkmcnt(7)
	v_mfma_f32_32x32x16_bf16 v[0:15], v[246:249], v[206:209], v[0:15]
	ds_read_b128 v[246:249], v235 offset:32256
	v_add_f32_e32 v191, v191, v94
	v_add_f32_e32 v192, v192, v95
	v_cvt_pk_bf16_f32 v200, v94, v95
	v_add_f32_e32 v191, v191, v96
	v_add_f32_e32 v192, v192, v97
	v_cvt_pk_bf16_f32 v201, v96, v97
	s_waitcnt lgkmcnt(0)
	s_barrier
	s_cmp_lt_u32 s4, 14
	s_cbranch_scc0 .Lda_nok
	s_lshl_b32 s18, s3, 15
	s_add_u32 s18, s18, s28
	s_addc_u32 s19, s29, 0
	global_load_dwordx4 v[130:133], v251, s[18:19]
	s_add_u32 s18, s18, 0x2000
	s_addc_u32 s19, s19, 0
	global_load_dwordx4 v[134:137], v251, s[18:19]
	s_add_u32 s18, s18, 0x2000
	s_addc_u32 s19, s19, 0
	global_load_dwordx4 v[138:141], v251, s[18:19]
	s_add_u32 s18, s18, 0x2000
	s_addc_u32 s19, s19, 0
	global_load_dwordx4 v[142:145], v251, s[18:19]
